# younger-workgroup priority raise kept through the FF1 epilogue (reset at tile end) in addition to the K-loop raise on all four GEMMs
# baseline (speedup 1.0000x reference)
gp151_skip:
.LBB0_151:
	s_and_b32 s8, s7, 0x8000
	s_xor_b32 s9, s8, 0x8000
	v_add_u32_e32 v79, s9, v74
	v_lshl_add_u64 v[80:81], v[64:65], 0, s[4:5]
	v_readfirstlane_b32 s9, v79
	v_lshl_add_u64 v[82:83], v[80:81], 0, s[28:29]
	s_mov_b32 m0, s9
	v_lshl_add_u64 v[84:85], v[66:67], 0, s[4:5]
	global_load_lds_dwordx4 v[82:83], off
	v_add_u32_e32 v82, 0x4000, v79
	v_lshl_add_u64 v[86:87], v[84:85], 0, s[28:29]
	v_readfirstlane_b32 s9, v82
	s_mov_b32 m0, s9
	v_lshl_add_u64 v[82:83], v[80:81], 0, s[10:11]
	global_load_lds_dwordx4 v[86:87], off
	v_add_u32_e32 v86, 0x1000, v79
	s_nop 0
	v_readfirstlane_b32 s9, v86
	v_add_u32_e32 v86, 0x5000, v79
	s_mov_b32 m0, s9
	v_readfirstlane_b32 s9, v86
	v_add_u32_e32 v86, 0x2000, v79
	global_load_lds_dwordx4 v[82:83], off
	v_lshl_add_u64 v[82:83], v[84:85], 0, s[10:11]
	s_mov_b32 m0, s9
	v_readfirstlane_b32 s9, v86
	v_add_u32_e32 v86, 0x6000, v79
	global_load_lds_dwordx4 v[82:83], off
	v_lshl_add_u64 v[82:83], v[80:81], 0, s[14:15]
	s_mov_b32 m0, s9
	v_readfirstlane_b32 s9, v86
	global_load_lds_dwordx4 v[82:83], off
	v_lshl_add_u64 v[82:83], v[84:85], 0, s[14:15]
	s_mov_b32 m0, s9
	v_lshl_add_u64 v[80:81], v[80:81], 0, s[12:13]
	global_load_lds_dwordx4 v[82:83], off
	v_add_u32_e32 v82, 0x3000, v79
	v_add_u32_e32 v79, 0x7000, v79
	v_readfirstlane_b32 s9, v82
	s_mov_b32 m0, s9
	v_readfirstlane_b32 s9, v79
	global_load_lds_dwordx4 v[80:81], off
	v_lshl_add_u64 v[80:81], v[84:85], 0, s[12:13]
	s_mov_b32 m0, s9
	v_or_b32_e32 v79, s8, v76
	global_load_lds_dwordx4 v[80:81], off
	v_add_u32_e32 v100, v79, v75
	v_add_u32_e32 v79, v79, v77
	ds_read_b128 v[80:83], v100
	ds_read_b128 v[84:87], v100 offset:2048
	ds_read_b128 v[88:91], v79 offset:16384
	ds_read_b128 v[92:95], v79 offset:18432
	ds_read_b128 v[96:99], v100 offset:4096
	ds_read_b128 v[100:103], v100 offset:6144
	ds_read_b128 v[104:107], v79 offset:20480
	ds_read_b128 v[108:111], v79 offset:22528
	v_or_b32_e32 v79, s8, v78
	v_add_u32_e32 v132, v79, v75
	v_add_u32_e32 v79, v79, v77
	ds_read_b128 v[112:115], v132
	ds_read_b128 v[116:119], v132 offset:2048
	ds_read_b128 v[120:123], v79 offset:16384
	ds_read_b128 v[124:127], v79 offset:18432
	ds_read_b128 v[128:131], v132 offset:4096
	ds_read_b128 v[132:135], v132 offset:6144
	ds_read_b128 v[146:149], v79 offset:20480
	ds_read_b128 v[150:153], v79 offset:22528
	s_waitcnt lgkmcnt(0)
	v_mfma_f32_16x16x32_bf16 v[60:63], v[80:83], v[88:91], v[60:63]
	v_mfma_f32_16x16x32_bf16 v[56:59], v[80:83], v[92:95], v[56:59]
	v_mfma_f32_16x16x32_bf16 v[52:55], v[80:83], v[104:107], v[52:55]
	v_mfma_f32_16x16x32_bf16 v[48:51], v[80:83], v[108:111], v[48:51]
	v_mfma_f32_16x16x32_bf16 v[44:47], v[84:87], v[88:91], v[44:47]
	v_mfma_f32_16x16x32_bf16 v[40:43], v[84:87], v[92:95], v[40:43]
	v_mfma_f32_16x16x32_bf16 v[36:39], v[84:87], v[104:107], v[36:39]
	v_mfma_f32_16x16x32_bf16 v[32:35], v[84:87], v[108:111], v[32:35]
	v_mfma_f32_16x16x32_bf16 v[28:31], v[96:99], v[88:91], v[28:31]
	v_mfma_f32_16x16x32_bf16 v[24:27], v[96:99], v[92:95], v[24:27]
	v_mfma_f32_16x16x32_bf16 v[20:23], v[96:99], v[104:107], v[20:23]
	v_mfma_f32_16x16x32_bf16 v[16:19], v[96:99], v[108:111], v[16:19]
	v_mfma_f32_16x16x32_bf16 v[12:15], v[100:103], v[88:91], v[12:15]
	v_mfma_f32_16x16x32_bf16 v[8:11], v[100:103], v[92:95], v[8:11]
	v_mfma_f32_16x16x32_bf16 v[4:7], v[100:103], v[104:107], v[4:7]
	v_mfma_f32_16x16x32_bf16 v[0:3], v[100:103], v[108:111], v[0:3]
	v_mfma_f32_16x16x32_bf16 v[60:63], v[112:115], v[120:123], v[60:63]
	v_mfma_f32_16x16x32_bf16 v[56:59], v[112:115], v[124:127], v[56:59]
	v_mfma_f32_16x16x32_bf16 v[52:55], v[112:115], v[146:149], v[52:55]
	v_mfma_f32_16x16x32_bf16 v[48:51], v[112:115], v[150:153], v[48:51]
	v_mfma_f32_16x16x32_bf16 v[44:47], v[116:119], v[120:123], v[44:47]
	v_mfma_f32_16x16x32_bf16 v[40:43], v[116:119], v[124:127], v[40:43]
	v_mfma_f32_16x16x32_bf16 v[36:39], v[116:119], v[146:149], v[36:39]
	v_mfma_f32_16x16x32_bf16 v[32:35], v[116:119], v[150:153], v[32:35]
	v_mfma_f32_16x16x32_bf16 v[28:31], v[128:131], v[120:123], v[28:31]
	v_mfma_f32_16x16x32_bf16 v[24:27], v[128:131], v[124:127], v[24:27]
	v_mfma_f32_16x16x32_bf16 v[20:23], v[128:131], v[146:149], v[20:23]
	v_mfma_f32_16x16x32_bf16 v[16:19], v[128:131], v[150:153], v[16:19]
	v_mfma_f32_16x16x32_bf16 v[12:15], v[132:135], v[120:123], v[12:15]
	v_mfma_f32_16x16x32_bf16 v[8:11], v[132:135], v[124:127], v[8:11]
	v_mfma_f32_16x16x32_bf16 v[4:7], v[132:135], v[146:149], v[4:7]
	v_mfma_f32_16x16x32_bf16 v[0:3], v[132:135], v[150:153], v[0:3]
	s_add_i32 s7, s7, 0x8000
	s_waitcnt vmcnt(0)
	s_add_u32 s4, s4, 0x80
	s_addc_u32 s5, s5, 0
	s_cmpk_lg_i32 s4, 0x780
	s_barrier
	s_cbranch_scc1 .LBB0_151
	v_add_u32_e32 v74, v78, v77
	v_add_u32_e32 v102, v78, v75
	v_add_u32_e32 v122, v76, v77
	v_add_u32_e32 v130, v76, v75
	ds_read_b128 v[64:67], v74 offset:55296
	ds_read_b128 v[78:81], v74 offset:53248
	ds_read_b128 v[82:85], v102 offset:38912
	ds_read_b128 v[86:89], v102 offset:36864
	ds_read_b128 v[90:93], v74 offset:51200
	ds_read_b128 v[94:97], v74 offset:49152
	ds_read_b128 v[98:101], v102 offset:34816
	ds_read_b128 v[102:105], v102 offset:32768
	ds_read_b128 v[74:77], v122 offset:55296
	ds_read_b128 v[106:109], v122 offset:53248
	ds_read_b128 v[110:113], v130 offset:38912
	ds_read_b128 v[114:117], v130 offset:36864
	ds_read_b128 v[118:121], v122 offset:51200
	ds_read_b128 v[122:125], v122 offset:49152
	ds_read_b128 v[126:129], v130 offset:34816
	ds_read_b128 v[130:133], v130 offset:32768
	v_and_b32_e32 v134, 64, v69
	s_waitcnt lgkmcnt(0)
	v_mfma_f32_16x16x32_bf16 v[60:63], v[130:133], v[122:125], v[60:63]
	v_mfma_f32_16x16x32_bf16 v[56:59], v[130:133], v[118:121], v[56:59]
	v_mfma_f32_16x16x32_bf16 v[52:55], v[130:133], v[106:109], v[52:55]
	v_mfma_f32_16x16x32_bf16 v[48:51], v[130:133], v[74:77], v[48:51]
	v_mfma_f32_16x16x32_bf16 v[44:47], v[126:129], v[122:125], v[44:47]
	v_mfma_f32_16x16x32_bf16 v[40:43], v[126:129], v[118:121], v[40:43]
	v_mfma_f32_16x16x32_bf16 v[36:39], v[126:129], v[106:109], v[36:39]
	v_mfma_f32_16x16x32_bf16 v[32:35], v[126:129], v[74:77], v[32:35]
	v_mfma_f32_16x16x32_bf16 v[28:31], v[114:117], v[122:125], v[28:31]
	v_mfma_f32_16x16x32_bf16 v[24:27], v[114:117], v[118:121], v[24:27]
	v_mfma_f32_16x16x32_bf16 v[20:23], v[114:117], v[106:109], v[20:23]
	v_mfma_f32_16x16x32_bf16 v[16:19], v[114:117], v[74:77], v[16:19]
	v_mfma_f32_16x16x32_bf16 v[12:15], v[110:113], v[122:125], v[12:15]
	v_mfma_f32_16x16x32_bf16 v[8:11], v[110:113], v[118:121], v[8:11]
	v_mfma_f32_16x16x32_bf16 v[4:7], v[110:113], v[106:109], v[4:7]
	v_mfma_f32_16x16x32_bf16 v[0:3], v[110:113], v[74:77], v[0:3]
	v_mfma_f32_16x16x32_bf16 v[60:63], v[102:105], v[94:97], v[60:63]
	v_mfma_f32_16x16x32_bf16 v[56:59], v[102:105], v[90:93], v[56:59]
	v_mfma_f32_16x16x32_bf16 v[52:55], v[102:105], v[78:81], v[52:55]
	v_mfma_f32_16x16x32_bf16 v[48:51], v[102:105], v[64:67], v[48:51]
	v_mfma_f32_16x16x32_bf16 v[44:47], v[98:101], v[94:97], v[44:47]
	v_mfma_f32_16x16x32_bf16 v[40:43], v[98:101], v[90:93], v[40:43]
	v_mfma_f32_16x16x32_bf16 v[36:39], v[98:101], v[78:81], v[36:39]
	v_mfma_f32_16x16x32_bf16 v[32:35], v[98:101], v[64:67], v[32:35]
	v_mfma_f32_16x16x32_bf16 v[28:31], v[86:89], v[94:97], v[28:31]
	v_mfma_f32_16x16x32_bf16 v[24:27], v[86:89], v[90:93], v[24:27]
	v_mfma_f32_16x16x32_bf16 v[20:23], v[86:89], v[78:81], v[20:23]
	v_mfma_f32_16x16x32_bf16 v[16:19], v[86:89], v[64:67], v[16:19]
	v_mfma_f32_16x16x32_bf16 v[12:15], v[82:85], v[94:97], v[12:15]
	v_mfma_f32_16x16x32_bf16 v[8:11], v[82:85], v[90:93], v[8:11]
	v_mfma_f32_16x16x32_bf16 v[4:7], v[82:85], v[78:81], v[4:7]
	v_mfma_f32_16x16x32_bf16 v[0:3], v[82:85], v[64:67], v[0:3]
	s_movk_i32 s4, 0x2400
	v_max_f32_e32 v60, v60, v60
	v_max_f32_e32 v56, v56, v56
	v_max_f32_e32 v52, v52, v52
	v_max_f32_e32 v48, v48, v48
	v_max_f32_e32 v44, v44, v44
	v_max_f32_e32 v40, v40, v40
	v_max_f32_e32 v36, v36, v36
	v_max_f32_e32 v32, v32, v32
	v_max_f32_e32 v28, v28, v28
	v_max_f32_e32 v24, v24, v24
	v_max_f32_e32 v20, v20, v20
	v_max_f32_e32 v16, v16, v16
	v_max_f32_e32 v12, v12, v12
	v_max_f32_e32 v8, v8, v8
	v_max_f32_e32 v4, v4, v4
	v_max_f32_e32 v0, v0, v0
	v_mul_lo_u32 v64, v72, s4
	v_max_f32_e32 v60, 0, v60
	v_max_f32_e32 v61, v61, v61
	v_max_f32_e32 v56, 0, v56
	v_max_f32_e32 v57, v57, v57
	v_max_f32_e32 v52, 0, v52
	v_max_f32_e32 v53, v53, v53
	v_max_f32_e32 v48, 0, v48
	v_max_f32_e32 v49, v49, v49
	v_max_f32_e32 v44, 0, v44
	v_max_f32_e32 v45, v45, v45
	v_max_f32_e32 v40, 0, v40
	v_max_f32_e32 v41, v41, v41
	v_max_f32_e32 v36, 0, v36
	v_max_f32_e32 v37, v37, v37
	v_max_f32_e32 v32, 0, v32
	v_max_f32_e32 v33, v33, v33
	v_max_f32_e32 v28, 0, v28
	v_max_f32_e32 v29, v29, v29
	v_max_f32_e32 v24, 0, v24
	v_max_f32_e32 v25, v25, v25
	v_max_f32_e32 v20, 0, v20
	v_max_f32_e32 v21, v21, v21
	v_max_f32_e32 v16, 0, v16
	v_max_f32_e32 v17, v17, v17
	v_max_f32_e32 v12, 0, v12
	v_max_f32_e32 v13, v13, v13
	v_max_f32_e32 v8, 0, v8
	v_max_f32_e32 v9, v9, v9
	v_max_f32_e32 v4, 0, v4
	v_max_f32_e32 v5, v5, v5
	v_max_f32_e32 v0, 0, v0
	v_max_f32_e32 v1, v1, v1
	v_lshl_or_b32 v65, v73, 1, v64
	v_mul_f32_e32 v60, v60, v60
	v_max_f32_e32 v61, 0, v61
	v_max_f32_e32 v62, v62, v62
	s_movk_i32 s4, 0x240
	v_mul_f32_e32 v56, v56, v56
	v_max_f32_e32 v57, 0, v57
	v_max_f32_e32 v58, v58, v58
	v_mul_f32_e32 v52, v52, v52
	v_max_f32_e32 v53, 0, v53
	v_max_f32_e32 v54, v54, v54
	v_mul_f32_e32 v48, v48, v48
	v_max_f32_e32 v49, 0, v49
	v_max_f32_e32 v50, v50, v50
	v_mul_f32_e32 v44, v44, v44
	v_max_f32_e32 v45, 0, v45
	v_max_f32_e32 v46, v46, v46
	v_mul_f32_e32 v40, v40, v40
	v_max_f32_e32 v41, 0, v41
	v_max_f32_e32 v42, v42, v42
	v_mul_f32_e32 v36, v36, v36
	v_max_f32_e32 v37, 0, v37
	v_max_f32_e32 v38, v38, v38
	v_mul_f32_e32 v32, v32, v32
	v_max_f32_e32 v33, 0, v33
	v_max_f32_e32 v34, v34, v34
	v_mul_f32_e32 v28, v28, v28
	v_max_f32_e32 v29, 0, v29
	v_max_f32_e32 v30, v30, v30
	v_mul_f32_e32 v24, v24, v24
	v_max_f32_e32 v25, 0, v25
	v_max_f32_e32 v26, v26, v26
	v_mul_f32_e32 v20, v20, v20
	v_max_f32_e32 v21, 0, v21
	v_max_f32_e32 v22, v22, v22
	v_mul_f32_e32 v16, v16, v16
	v_max_f32_e32 v17, 0, v17
	v_max_f32_e32 v18, v18, v18
	v_mul_f32_e32 v12, v12, v12
	v_max_f32_e32 v13, 0, v13
	v_max_f32_e32 v14, v14, v14
	v_mul_f32_e32 v8, v8, v8
	v_max_f32_e32 v9, 0, v9
	v_max_f32_e32 v10, v10, v10
	v_mul_f32_e32 v4, v4, v4
	v_max_f32_e32 v5, 0, v5
	v_max_f32_e32 v6, v6, v6
	v_mul_f32_e32 v0, v0, v0
	v_max_f32_e32 v1, 0, v1
	v_max_f32_e32 v2, v2, v2
	v_mul_f32_e32 v61, v61, v61
	v_max_f32_e32 v62, 0, v62
	v_max_f32_e32 v63, v63, v63
	v_cvt_pk_bf16_f32 v60, v60, s0
	v_mad_u32_u24 v65, v71, s4, v65
	v_mul_f32_e32 v57, v57, v57
	v_max_f32_e32 v58, 0, v58
	v_max_f32_e32 v59, v59, v59
	v_cvt_pk_bf16_f32 v56, v56, s0
	v_mul_f32_e32 v53, v53, v53
	v_max_f32_e32 v54, 0, v54
	v_max_f32_e32 v55, v55, v55
	v_cvt_pk_bf16_f32 v52, v52, s0
	v_mul_f32_e32 v49, v49, v49
	v_max_f32_e32 v50, 0, v50
	v_max_f32_e32 v51, v51, v51
	v_cvt_pk_bf16_f32 v48, v48, s0
	v_mul_f32_e32 v45, v45, v45
	v_max_f32_e32 v46, 0, v46
	v_max_f32_e32 v47, v47, v47
	v_cvt_pk_bf16_f32 v44, v44, s0
	v_mul_f32_e32 v41, v41, v41
	v_max_f32_e32 v42, 0, v42
	v_max_f32_e32 v43, v43, v43
	v_cvt_pk_bf16_f32 v40, v40, s0
	v_mul_f32_e32 v37, v37, v37
	v_max_f32_e32 v38, 0, v38
	v_max_f32_e32 v39, v39, v39
	v_cvt_pk_bf16_f32 v36, v36, s0
	v_mul_f32_e32 v33, v33, v33
	v_max_f32_e32 v34, 0, v34
	v_max_f32_e32 v35, v35, v35
	v_cvt_pk_bf16_f32 v32, v32, s0
	v_mul_f32_e32 v29, v29, v29
	v_max_f32_e32 v30, 0, v30
	v_max_f32_e32 v31, v31, v31
	v_cvt_pk_bf16_f32 v28, v28, s0
	v_mul_f32_e32 v25, v25, v25
	v_max_f32_e32 v26, 0, v26
	v_max_f32_e32 v27, v27, v27
	v_cvt_pk_bf16_f32 v24, v24, s0
	v_mul_f32_e32 v21, v21, v21
	v_max_f32_e32 v22, 0, v22
	v_max_f32_e32 v23, v23, v23
	v_cvt_pk_bf16_f32 v20, v20, s0
	v_mul_f32_e32 v17, v17, v17
	v_max_f32_e32 v18, 0, v18
	v_max_f32_e32 v19, v19, v19
	v_cvt_pk_bf16_f32 v16, v16, s0
	v_mul_f32_e32 v13, v13, v13
	v_max_f32_e32 v14, 0, v14
	v_max_f32_e32 v15, v15, v15
	v_cvt_pk_bf16_f32 v12, v12, s0
	v_mul_f32_e32 v9, v9, v9
	v_max_f32_e32 v10, 0, v10
	v_max_f32_e32 v11, v11, v11
	v_cvt_pk_bf16_f32 v8, v8, s0
	v_mul_f32_e32 v5, v5, v5
	v_max_f32_e32 v6, 0, v6
	v_max_f32_e32 v7, v7, v7
	v_cvt_pk_bf16_f32 v4, v4, s0
	v_mul_f32_e32 v1, v1, v1
	v_max_f32_e32 v2, 0, v2
	v_max_f32_e32 v3, v3, v3
	v_cvt_pk_bf16_f32 v0, v0, s0
	s_waitcnt vmcnt(0)
	s_barrier
	v_mul_f32_e32 v62, v62, v62
	v_max_f32_e32 v63, 0, v63
	ds_write_b16 v65, v60
	v_cvt_pk_bf16_f32 v60, v61, s0
	v_mul_f32_e32 v58, v58, v58
	v_max_f32_e32 v59, 0, v59
	ds_write_b16 v65, v56 offset:32
	v_cvt_pk_bf16_f32 v56, v57, s0
	v_mul_f32_e32 v54, v54, v54
	v_max_f32_e32 v55, 0, v55
	ds_write_b16 v65, v52 offset:64
	v_cvt_pk_bf16_f32 v52, v53, s0
	v_mul_f32_e32 v50, v50, v50
	v_max_f32_e32 v51, 0, v51
	ds_write_b16 v65, v48 offset:96
	v_cvt_pk_bf16_f32 v48, v49, s0
	v_mul_f32_e32 v46, v46, v46
	v_max_f32_e32 v47, 0, v47
	ds_write_b16 v65, v44 offset:2304
	v_cvt_pk_bf16_f32 v44, v45, s0
	v_mul_f32_e32 v42, v42, v42
	v_max_f32_e32 v43, 0, v43
	ds_write_b16 v65, v40 offset:2336
	v_cvt_pk_bf16_f32 v40, v41, s0
	v_mul_f32_e32 v38, v38, v38
	v_max_f32_e32 v39, 0, v39
	ds_write_b16 v65, v36 offset:2368
	v_cvt_pk_bf16_f32 v36, v37, s0
	v_mul_f32_e32 v34, v34, v34
	v_max_f32_e32 v35, 0, v35
	ds_write_b16 v65, v32 offset:2400
	v_cvt_pk_bf16_f32 v32, v33, s0
	v_mul_f32_e32 v30, v30, v30
	v_max_f32_e32 v31, 0, v31
	ds_write_b16 v65, v28 offset:4608
	v_cvt_pk_bf16_f32 v28, v29, s0
	v_mul_f32_e32 v26, v26, v26
	v_max_f32_e32 v27, 0, v27
	ds_write_b16 v65, v24 offset:4640
	v_cvt_pk_bf16_f32 v24, v25, s0
	v_mul_f32_e32 v22, v22, v22
	v_max_f32_e32 v23, 0, v23
	ds_write_b16 v65, v20 offset:4672
	v_cvt_pk_bf16_f32 v20, v21, s0
	v_mul_f32_e32 v18, v18, v18
	v_max_f32_e32 v19, 0, v19
	ds_write_b16 v65, v16 offset:4704
	v_cvt_pk_bf16_f32 v16, v17, s0
	v_mul_f32_e32 v14, v14, v14
	v_max_f32_e32 v15, 0, v15
	ds_write_b16 v65, v12 offset:6912
	v_cvt_pk_bf16_f32 v12, v13, s0
	v_mul_f32_e32 v10, v10, v10
	v_max_f32_e32 v11, 0, v11
	ds_write_b16 v65, v8 offset:6944
	v_cvt_pk_bf16_f32 v8, v9, s0
	v_mul_f32_e32 v6, v6, v6
	v_max_f32_e32 v7, 0, v7
	ds_write_b16 v65, v4 offset:6976
	v_cvt_pk_bf16_f32 v4, v5, s0
	v_mul_f32_e32 v2, v2, v2
	v_max_f32_e32 v3, 0, v3
	ds_write_b16 v65, v0 offset:7008
	v_cvt_pk_bf16_f32 v0, v1, s0
	v_mul_f32_e32 v63, v63, v63
	ds_write_b16 v65, v60 offset:144
	v_cvt_pk_bf16_f32 v60, v62, s0
	v_mul_f32_e32 v59, v59, v59
	ds_write_b16 v65, v56 offset:176
	v_cvt_pk_bf16_f32 v56, v58, s0
	v_mul_f32_e32 v55, v55, v55
	ds_write_b16 v65, v52 offset:208
	v_cvt_pk_bf16_f32 v52, v54, s0
	v_mul_f32_e32 v51, v51, v51
	ds_write_b16 v65, v48 offset:240
	v_cvt_pk_bf16_f32 v48, v50, s0
	v_mul_f32_e32 v47, v47, v47
	ds_write_b16 v65, v44 offset:2448
	v_cvt_pk_bf16_f32 v44, v46, s0
	v_mul_f32_e32 v43, v43, v43
	ds_write_b16 v65, v40 offset:2480
	v_cvt_pk_bf16_f32 v40, v42, s0
	v_mul_f32_e32 v39, v39, v39
	ds_write_b16 v65, v36 offset:2512
	v_cvt_pk_bf16_f32 v36, v38, s0
	v_mul_f32_e32 v35, v35, v35
	ds_write_b16 v65, v32 offset:2544
	v_cvt_pk_bf16_f32 v32, v34, s0
	v_mul_f32_e32 v31, v31, v31
	ds_write_b16 v65, v28 offset:4752
	v_cvt_pk_bf16_f32 v28, v30, s0
	v_mul_f32_e32 v27, v27, v27
	ds_write_b16 v65, v24 offset:4784
	v_cvt_pk_bf16_f32 v24, v26, s0
	v_mul_f32_e32 v23, v23, v23
	ds_write_b16 v65, v20 offset:4816
	v_cvt_pk_bf16_f32 v20, v22, s0
	v_mul_f32_e32 v19, v19, v19
	ds_write_b16 v65, v16 offset:4848
	v_cvt_pk_bf16_f32 v16, v18, s0
	v_mul_f32_e32 v15, v15, v15
	ds_write_b16 v65, v12 offset:7056
	v_cvt_pk_bf16_f32 v12, v14, s0
	v_mul_f32_e32 v11, v11, v11
	ds_write_b16 v65, v8 offset:7088
	v_cvt_pk_bf16_f32 v8, v10, s0
	v_mul_f32_e32 v7, v7, v7
	ds_write_b16 v65, v4 offset:7120
	v_cvt_pk_bf16_f32 v4, v6, s0
	v_mul_f32_e32 v3, v3, v3
	ds_write_b16 v65, v0 offset:7152
	v_cvt_pk_bf16_f32 v0, v2, s0
	v_add_u32_e32 v5, s1, v70
	s_ashr_i32 s1, s0, 31
	v_readlane_b32 s36, v246, 25
	ds_write_b16 v65, v60 offset:288
	v_cvt_pk_bf16_f32 v60, v63, s0
	ds_write_b16 v65, v56 offset:320
	v_cvt_pk_bf16_f32 v56, v59, s0
	ds_write_b16 v65, v52 offset:352
	v_cvt_pk_bf16_f32 v52, v55, s0
	ds_write_b16 v65, v48 offset:384
	v_cvt_pk_bf16_f32 v48, v51, s0
	ds_write_b16 v65, v44 offset:2592
	v_cvt_pk_bf16_f32 v44, v47, s0
	ds_write_b16 v65, v40 offset:2624
	v_cvt_pk_bf16_f32 v40, v43, s0
	ds_write_b16 v65, v36 offset:2656
	v_cvt_pk_bf16_f32 v36, v39, s0
	ds_write_b16 v65, v32 offset:2688
	v_cvt_pk_bf16_f32 v32, v35, s0
	ds_write_b16 v65, v28 offset:4896
	v_cvt_pk_bf16_f32 v28, v31, s0
	ds_write_b16 v65, v24 offset:4928
	v_cvt_pk_bf16_f32 v24, v27, s0
	ds_write_b16 v65, v20 offset:4960
	v_cvt_pk_bf16_f32 v20, v23, s0
	ds_write_b16 v65, v16 offset:4992
	v_cvt_pk_bf16_f32 v16, v19, s0
	ds_write_b16 v65, v12 offset:7200
	v_cvt_pk_bf16_f32 v12, v15, s0
	ds_write_b16 v65, v8 offset:7232
	v_cvt_pk_bf16_f32 v8, v11, s0
	ds_write_b16 v65, v4 offset:7264
	v_cvt_pk_bf16_f32 v4, v7, s0
	ds_write_b16 v65, v0 offset:7296
	v_cvt_pk_bf16_f32 v0, v3, s0
	s_lshl_b64 s[0:1], s[0:1], 1
	v_readlane_b32 s38, v246, 27
	ds_write_b16 v65, v0 offset:7440
	v_lshlrev_b32_e32 v0, 4, v69
	v_readlane_b32 s39, v246, 28
	s_add_u32 s0, s38, s0
	v_and_b32_e32 v0, 0x70, v0
	s_addc_u32 s1, s39, s1
	v_lshlrev_b32_e32 v136, 1, v134
	ds_write_b16 v65, v4 offset:7408
	v_or_b32_e32 v4, v64, v0
	v_lshl_add_u64 v[2:3], s[0:1], 0, v[136:137]
	s_movk_i32 s0, 0x90
	ds_write_b16 v65, v60 offset:432
	ds_write_b16 v65, v56 offset:464
	ds_write_b16 v65, v52 offset:496
	ds_write_b16 v65, v48 offset:528
	ds_write_b16 v65, v44 offset:2736
	ds_write_b16 v65, v40 offset:2768
	ds_write_b16 v65, v36 offset:2800
	ds_write_b16 v65, v32 offset:2832
	ds_write_b16 v65, v28 offset:5040
	ds_write_b16 v65, v24 offset:5072
	ds_write_b16 v65, v20 offset:5104
	ds_write_b16 v65, v16 offset:5136
	ds_write_b16 v65, v12 offset:7344
	ds_write_b16 v65, v8 offset:7376
	v_mov_b32_e32 v1, v137
	v_mad_u32_u24 v12, v68, s0, v4
	v_lshl_add_u64 v[8:9], v[2:3], 0, v[0:1]
	ds_read_b128 v[0:3], v12
	v_or_b32_e32 v13, v5, v68
	ds_read_b128 v[4:7], v12 offset:1152
	s_movk_i32 s4, 0x2080
	v_mad_i64_i32 v[10:11], s[0:1], v13, s4, v[8:9]
	s_waitcnt lgkmcnt(1)
	global_store_dwordx4 v[10:11], v[0:3], off
	s_add_i32 s6, s6, 1
	s_movk_i32 s36, 0x880
	v_or_b32_e32 v0, 8, v13
	v_mad_i64_i32 v[0:1], s[0:1], v0, s4, v[8:9]
	s_waitcnt lgkmcnt(0)
	global_store_dwordx4 v[0:1], v[4:7], off
	ds_read_b128 v[0:3], v12 offset:2304
	v_readlane_b32 s37, v246, 26
	v_or_b32_e32 v4, 16, v13
	v_mad_i64_i32 v[10:11], s[0:1], v4, s4, v[8:9]
	ds_read_b128 v[4:7], v12 offset:3456
	s_waitcnt lgkmcnt(1)
	global_store_dwordx4 v[10:11], v[0:3], off
	v_readlane_b32 s40, v246, 29
	v_readlane_b32 s41, v246, 30
	v_or_b32_e32 v0, 24, v13
	v_mad_i64_i32 v[0:1], s[0:1], v0, s4, v[8:9]
	s_waitcnt lgkmcnt(0)
	global_store_dwordx4 v[0:1], v[4:7], off
	ds_read_b128 v[0:3], v12 offset:4608
	v_readlane_b32 s42, v246, 31
	v_or_b32_e32 v4, 32, v13
	v_mad_i64_i32 v[10:11], s[0:1], v4, s4, v[8:9]
	ds_read_b128 v[4:7], v12 offset:5760
	s_waitcnt lgkmcnt(1)
	global_store_dwordx4 v[10:11], v[0:3], off
	v_readlane_b32 s43, v246, 32
	v_readlane_b32 s44, v246, 33
	v_or_b32_e32 v0, 40, v13
	v_mad_i64_i32 v[0:1], s[0:1], v0, s4, v[8:9]
	s_waitcnt lgkmcnt(0)
	global_store_dwordx4 v[0:1], v[4:7], off
	ds_read_b128 v[0:3], v12 offset:6912
	v_readlane_b32 s45, v246, 34
	v_or_b32_e32 v4, 48, v13
	v_mad_i64_i32 v[10:11], s[0:1], v4, s4, v[8:9]
	ds_read_b128 v[4:7], v12 offset:8064
	s_waitcnt lgkmcnt(1)
	global_store_dwordx4 v[10:11], v[0:3], off
	v_readlane_b32 s46, v246, 35
	v_readlane_b32 s47, v246, 36
	v_or_b32_e32 v0, 56, v13
	v_mad_i64_i32 v[0:1], s[0:1], v0, s4, v[8:9]
	s_mov_b64 s[4:5], 0
	v_readlane_b32 s48, v246, 37
	v_readlane_b32 s49, v246, 38
	v_readlane_b32 s50, v246, 39
	v_readlane_b32 s51, v246, 40
	s_waitcnt lgkmcnt(0)
	global_store_dwordx4 v[0:1], v[4:7], off
	s_barrier
	s_setprio 0
	s_branch .LBB0_141
